# GEMM-in: zero-padded 49th column tile dropped (12 rounds instead of 13); the 32 dt columns of prompt rows computed by a single-pass copy of the skinny GEMM block
# baseline (speedup 1.0000x reference)
; #define TID() ({ int t__; asm volatile("v_mbcnt_lo_u32_b32 %0, -1, 0\n\tv_mbcnt_hi_u32_b32 %0, -1, %0" : "=v"(t__)); (wave_u << 6) | t__; })
;     __host__ __device__ bool next(int i, Unit& u) const {
;         const long L = (long)i * G + c; if (L >= nwg) return false;
;         int wgid = (int)L; { const int q = nwg / NXCD, r = nwg % NXCD, xcd = wgid % NXCD, off = wgid / NXCD; wgid = (xcd < r ? xcd * (q + 1) : r * (q + 1) + (xcd - r) * q) + off; }
;         const int nig = WGM * nN, gid = wgid / nig, fm = gid * WGM, gsz = (nM - fm) < WGM ? (nM - fm) : WGM;
;         u.pm = fm + ((wgid % nig) % gsz); u.pn = (wgid % nig) / gsz; return true;
; __global__ __launch_bounds__(NTHREADS, 2) void k_mega(P p) {
;     ...
;             pg8::Gemm g{(const bf16*)(w + WS_H), (const bf16*)(wl + WO_IN), MP, LDP, D}; pg8::StaticOrder S; S.init(MP, LDP, G, (int)blockIdx.x);
;             pg8::EpiBf16<0> E{(bf16*)(w + WS_PROJ), LDP};
;             pg8::gemm_phase<pg8::EpiBf16<0>, pg8::StaticOrder>(lds, g, S, E, nullptr, TID());
.LBB0_180:
	v_writelane_b32 v253, s56, 48
	v_writelane_b32 v254, s54, 0
	s_nop 0
	v_writelane_b32 v253, s57, 49
	v_writelane_b32 v253, s58, 50
	v_writelane_b32 v253, s59, 51
	v_writelane_b32 v253, s60, 52
	v_writelane_b32 v253, s61, 53
	v_writelane_b32 v253, s62, 54
	v_writelane_b32 v253, s63, 55
	v_writelane_b32 v253, s64, 56
	v_writelane_b32 v253, s65, 57
	v_writelane_b32 v253, s66, 58
	v_writelane_b32 v253, s67, 59
	v_writelane_b32 v253, s68, 60
	v_writelane_b32 v253, s69, 61
	v_writelane_b32 v253, s70, 62
	v_writelane_b32 v253, s71, 63
	s_or_b64 exec, exec, s[2:3]
	s_cmpk_lt_i32 s52, 0xc00
	s_cselect_b64 s[0:1], -1, 0
	v_writelane_b32 v254, s0, 1
	s_ashr_i32 s53, s52, 31
	s_ashr_i32 s91, s90, 31
	v_writelane_b32 v254, s1, 2
	s_lshr_b32 s0, s53, 29
	s_add_i32 s0, s52, s0
	s_ashr_i32 s4, s0, 3
	s_and_b32 s0, s0, -8
	s_sub_i32 s5, s52, s0
	s_sub_i32 s0, s90, 64
	s_cmp_gt_i32 s90, 64
	s_cselect_b32 s1, 0xffffffc0, 0
	s_cselect_b32 s8, s0, s90
	s_add_i32 s9, s1, s52
	s_cmp_gt_i32 s9, -1
	s_cselect_b64 s[0:1], -1, 0
	s_cmp_lt_i32 s9, s8
	s_cselect_b64 s[2:3], -1, 0
	s_and_b64 s[0:1], s[0:1], s[2:3]
	s_cmpk_lt_u32 s9, 0x188
	s_cselect_b64 s[2:3], -1, 0
	s_and_b64 s[0:1], s[0:1], s[2:3]
	v_writelane_b32 v254, s0, 3
	s_bitcmp1_b32 s52, 3
	v_readlane_b32 s12, v253, 0
	v_writelane_b32 v254, s1, 4
	s_cselect_b64 s[0:1], -1, 0
	v_writelane_b32 v254, s0, 5
	s_cmpk_lt_i32 s52, 0x100
	v_readlane_b32 s18, v253, 6
	v_writelane_b32 v254, s1, 6
	s_cselect_b64 s[0:1], -1, 0
	v_writelane_b32 v254, s0, 7
	v_readlane_b32 s19, v253, 7
	v_readlane_b32 s13, v253, 1
	v_writelane_b32 v254, s1, 8
	s_add_u32 s0, s18, 0x7080000
	v_writelane_b32 v254, s0, 9
	s_addc_u32 s0, s19, 0
	s_cmpk_lt_i32 s52, 0x400
	v_writelane_b32 v254, s0, 10
	s_cselect_b64 s[0:1], -1, 0
	v_writelane_b32 v254, s0, 11
	s_lshl_b32 s2, s52, 2
	s_ashr_i32 s3, s2, 31
	v_writelane_b32 v254, s1, 12
	s_mov_b32 s0, s2
	v_writelane_b32 v254, s0, 13
	v_readlane_b32 s14, v253, 2
	v_readlane_b32 s15, v253, 3
	v_writelane_b32 v254, s1, 14
	s_lshl_b64 s[0:1], s[2:3], 15
	v_writelane_b32 v254, s0, 15
	s_mul_hi_i32 s61, s96, 0x18000
	v_writelane_b32 v255, s9, 0
	v_writelane_b32 v254, s1, 16
	s_add_u32 s0, s18, 0x17200000
	v_writelane_b32 v254, s0, 17
	s_addc_u32 s0, s19, 0
	v_writelane_b32 v254, s0, 18
	s_add_u32 s0, s18, 0x37200000
	v_writelane_b32 v254, s0, 19
	s_addc_u32 s0, s19, 0
	s_lshl_b64 s[10:11], s[52:53], 16
	v_writelane_b32 v254, s0, 20
	s_add_u32 s0, s18, 0x4080000
	v_writelane_b32 v254, s0, 21
	s_addc_u32 s0, s19, 0
	v_writelane_b32 v254, s0, 22
	s_add_u32 s0, s18, 0x5080000
	v_writelane_b32 v254, s0, 23
	s_addc_u32 s0, s19, 0
	s_lshl_b32 s6, s5, 5
	s_cmp_gt_i32 s52, -1
	v_writelane_b32 v254, s0, 24
	s_cselect_b64 s[0:1], -1, 0
	s_cmp_lt_i32 s52, s90
	s_cselect_b64 s[2:3], -1, 0
	s_and_b64 s[0:1], s[0:1], s[2:3]
	s_cmpk_lt_u32 s52, 0x100
	s_cselect_b64 s[2:3], -1, 0
	s_and_b64 s[0:1], s[0:1], s[2:3]
	v_writelane_b32 v254, s0, 25
	s_movk_i32 s3, 0x181
	s_mul_i32 s2, s5, 0x81
	v_writelane_b32 v254, s1, 26
	s_lshl_b32 s0, s5, 7
	s_cmp_lt_i32 s5, 0
	s_cselect_b32 s3, s3, 0x180
	s_mul_i32 s1, s5, 33
	s_mul_i32 s3, s5, s3
	s_cselect_b32 s5, s1, s6
	s_cselect_b32 s2, s2, s0
	s_add_i32 s3, s3, s4
	s_mul_hi_i32 s0, s3, 0x55555556
	s_lshr_b32 s1, s0, 31
	s_ashr_i32 s0, s0, 6
	s_add_i32 s0, s0, s1
	s_mul_i32 s1, s0, 0xc0
	s_sub_i32 s1, s3, s1
	s_lshl_b32 s6, s0, 2
	s_bfe_u32 s0, s1, 0x2001d
	s_add_i32 s3, s1, s0
	s_sext_i32_i16 s7, s3
	s_and_b32 s3, s3, 0xfffc
	s_sub_i32 s1, s1, s3
	s_sext_i32_i16 s1, s1
	s_add_i32 s12, s6, s1
	s_ashr_i32 s1, s7, 2
	v_writelane_b32 v254, s1, 27
	s_mov_b32 s6, s12
	s_lshr_b32 s0, s7, 2
	s_ashr_i32 s13, s12, 31
	v_writelane_b32 v254, s6, 28
	s_bfe_i64 s[0:1], s[0:1], 0x100000
	s_lshl_b64 s[0:1], s[0:1], 19
	v_writelane_b32 v254, s7, 29
	s_lshl_b64 s[6:7], s[12:13], 19
	v_writelane_b32 v254, s6, 30
	s_add_i32 s2, s2, s4
	s_ashr_i32 s97, s96, 31
	v_writelane_b32 v254, s7, 31
	v_writelane_b32 v254, s0, 32
	s_lshl_b64 s[78:79], s[96:97], 14
	s_mul_i32 s60, s96, 0x18000
	v_writelane_b32 v254, s1, 33
	s_add_i32 s0, s5, s4
	s_ashr_i32 s1, s0, 31
	s_lshr_b32 s1, s1, 28
	s_add_i32 s1, s0, s1
	s_ashr_i32 s3, s1, 4
	s_and_b32 s1, s1, 0xfff0
	s_sub_i32 s1, s0, s1
	s_bfe_i32 s0, s1, 0x80000
	s_bfe_u32 s0, s0, 0x2000d
	s_add_i32 s5, s1, s0
	s_bfe_i32 s0, s5, 0x80000
	s_and_b32 s5, s5, 0xfc
	s_sub_i32 s1, s1, s5
	s_lshl_b32 s3, s3, 2
	s_sext_i32_i8 s1, s1
	s_sext_i32_i16 s6, s0
	s_add_i32 s12, s3, s1
; #define LAS __attribute__((address_space(3)))
; __device__ __forceinline__ void phase_recur1(const P& p, int l, LAS unsigned char* lds, int tid_in, int skip_hgrn1) {
;     unsigned char* ws = p.ws; asm volatile("" : "+s"(ws)); int tid_ = tid_in; asm volatile("" : "+v"(tid_)); const int tid = tid_, G = gridDim.x, wg = blockIdx.x;
;     RecurBufs rb{(bf16*)(ws + WS_PROJ), (bf16*)(ws + WS_XBCC), (float*)(ws + WS_DTV), (float*)(ws + WS_CUM), (float*)(ws + WS_CV), (float*)(ws + WS_SSEG), (float*)(ws + WS_DSEG),
;                  (float*)(ws + WS_HSEG), (float*)(ws + WS_TSEG), (bf16*)(ws + WS_OHG), (bf16*)(ws + WS_Y)};
;     const float* lbs_l = (const float*)(ws + WS_LBS) + l * 1024; float* out = p.out;
;     const float* hgn = p.in[I_HGN] + l * HG_DV;
;     const float* cw = p.in[I_CONVW] + (size_t)l * 4 * SSM_CH; const float* cb = p.in[I_CONVB] + l * SSM_CH; const float* dtb = p.in[I_DTB] + l * SSM_HEADS;
;     const float* alog = p.in[I_ALOG] + l * SSM_HEADS; const float* dsk = p.in[I_DSKIP] + l * SSM_HEADS; const float* ssmn = p.in[I_SSMN] + l * SSM_INNER;
	s_ashr_i32 s3, s2, 31
	s_ashr_i32 s1, s6, 2
	s_ashr_i32 s13, s12, 31
	s_lshr_b32 s3, s3, 26
	s_lshr_b32 s0, s6, 2
	v_writelane_b32 v254, s1, 34
	s_lshl_b64 s[6:7], s[12:13], 19
	s_add_i32 s3, s2, s3
	v_writelane_b32 v254, s6, 35
	s_bfe_i64 s[0:1], s[0:1], 0x100000
	s_ashr_i32 s4, s3, 6
	s_and_b32 s3, s3, 0xffc0
	v_writelane_b32 v254, s7, 36
	s_lshl_b64 s[6:7], s[0:1], 19
	s_sub_i32 s3, s2, s3
	v_writelane_b32 v254, s6, 37
	s_bfe_i32 s2, s3, 0x80000
	s_bfe_u32 s2, s2, 0x2000d
	v_writelane_b32 v254, s7, 38
	s_lshl_b64 s[6:7], s[12:13], 20
	v_writelane_b32 v254, s6, 39
	s_add_i32 s5, s3, s2
	s_bfe_i32 s2, s5, 0x80000
	v_writelane_b32 v254, s7, 40
	s_lshl_b64 s[6:7], s[0:1], 20
	s_and_b32 s5, s5, 0xfc
	v_writelane_b32 v254, s6, 41
	s_sub_i32 s3, s3, s5
	s_lshl_b32 s4, s4, 2
	v_writelane_b32 v254, s7, 42
	s_sext_i32_i16 s6, s2
	s_sext_i32_i8 s3, s3
	s_add_i32 s14, s4, s3
	s_ashr_i32 s3, s6, 2
	v_writelane_b32 v254, s3, 43
	s_mov_b32 s4, s14
	s_ashr_i32 s15, s14, 31
	v_writelane_b32 v254, s4, 44
	s_lshr_b32 s2, s6, 2
	s_bfe_i64 s[2:3], s[2:3], 0x100000
	v_writelane_b32 v254, s5, 45
	s_lshl_b64 s[4:5], s[14:15], 19
	v_writelane_b32 v254, s4, 46
	s_lshl_b64 s[2:3], s[2:3], 19
	s_lshl_b64 s[0:1], s[0:1], 21
	v_writelane_b32 v254, s5, 47
	v_writelane_b32 v254, s2, 48
	s_movk_i32 s51, 0x4000
	v_mov_b32_e32 v11, 0
	v_writelane_b32 v254, s3, 49
	s_mov_b32 s2, s12
	v_writelane_b32 v254, s2, 50
	v_mov_b32_e32 v176, 0x358637bd
	v_mov_b32_e32 v178, 0x3ecc95a3
	v_writelane_b32 v254, s3, 51
	s_lshl_b64 s[2:3], s[12:13], 21
	v_writelane_b32 v254, s2, 52
	v_mov_b32_e32 v148, 0x3f317218
	v_mov_b32_e32 v183, 0x7f800000
	v_writelane_b32 v254, s3, 53
	v_writelane_b32 v254, s0, 54
	s_lshl_b64 s[2:3], s[96:97], 11
	v_mov_b32_e32 v184, 0x7fc00000
	v_writelane_b32 v254, s1, 55
	v_readlane_b32 s0, v253, 47
	s_add_i32 s1, s0, 0x4000
	v_writelane_b32 v254, s1, 56
	v_writelane_b32 v254, s2, 57
	s_add_i32 s0, s0, 8
	v_mov_b32_e32 v185, 0xff800000
	v_writelane_b32 v254, s3, 58
	v_writelane_b32 v254, s0, 59
	s_lshl_b64 s[0:1], s[96:97], 15
	v_writelane_b32 v254, s0, 60
	v_mov_b32_e32 v186, 0x41b17218
	v_mov_b32_e32 v187, 0x42a00000
	v_writelane_b32 v254, s1, 61
	s_lshl_b64 s[0:1], s[96:97], 12
	v_writelane_b32 v254, s0, 62
	s_mov_b32 s33, 0x800000
	s_movk_i32 s77, 0x6200
	v_writelane_b32 v254, s1, 63
	s_lshl_b32 s0, s9, 5
	v_writelane_b32 v255, s0, 1
	v_writelane_b32 v255, s8, 2
	s_lshl_b32 s0, s8, 5
	v_writelane_b32 v255, s0, 3
	s_add_u32 s0, s18, s10
	v_writelane_b32 v255, s10, 4
	s_addc_u32 s1, s19, s11
	s_add_u32 s0, s0, 0x7200000
	v_writelane_b32 v255, s11, 5
	v_writelane_b32 v255, s0, 6
	s_addc_u32 s0, s1, 0
	v_writelane_b32 v255, s0, 7
	s_lshl_b32 s0, s52, 4
	v_writelane_b32 v255, s0, 8
	s_lshl_b32 s0, s90, 2
	v_writelane_b32 v255, s0, 9
	s_lshl_b32 s0, s52, 6
	v_writelane_b32 v255, s0, 10
	s_lshl_b32 s0, s90, 6
	v_writelane_b32 v255, s0, 11
	s_add_i32 s0, 0, 0x25f20
	v_writelane_b32 v255, s0, 12
	s_add_i32 s0, 0, 0x25f24
	v_writelane_b32 v255, s0, 13
	s_add_i32 s0, 0, 0x18c00
	v_writelane_b32 v255, s0, 14
	s_add_i32 s0, 0, 0x19000
	v_writelane_b32 v255, s0, 15
	s_add_i32 s0, 0, 0x10400
	v_writelane_b32 v255, s0, 16
	s_add_i32 s0, 0, 0x15400
	v_writelane_b32 v255, s0, 17
	s_add_i32 s0, 0, 0x15800
	v_writelane_b32 v255, s0, 18
	s_add_i32 s0, 0, 0x15600
	v_writelane_b32 v255, s0, 19
	s_add_i32 s0, 0, 0x21c00
	v_writelane_b32 v255, s0, 20
	s_lshl_b64 s[2:3], s[90:91], 16
	v_writelane_b32 v255, s2, 21
	s_add_i32 s76, 0, 0x21400
	s_add_i32 s88, 0, 0x21800
	v_writelane_b32 v255, s3, 22
	v_writelane_b32 v255, s60, 23
	s_movk_i32 s89, 0x410
	s_mov_b32 s54, 0x41a00000
	v_writelane_b32 v255, s61, 24
	v_writelane_b32 v255, s96, 25
	s_mov_b32 s81, 0x7f800000
	s_mov_b32 s75, 0x5040100
	v_writelane_b32 v255, s97, 26
	v_writelane_b32 v255, s78, 27
	s_mov_b32 s38, 0x17788000
	s_mov_b32 s39, 0x1784c000
	s_mov_b32 s55, 0x17789000
	s_mov_b32 s80, 0x1784d000
	s_mov_b32 s74, 0x3f317217
	s_mov_b32 s86, 0xc2a00000
	s_add_i32 s87, 0, 0x15c00
	s_mov_b32 s0, 0
	s_mov_b32 s65, 0
	s_mov_b64 s[94:95], 0x1000
	s_mov_b64 s[82:83], 0x80
	s_mov_b64 s[92:93], 0x3000
	s_mov_b64 s[84:85], 0x31000
	s_mov_b32 s40, 0xbfb8aa3b
	s_mov_b64 s[42:43], 0x10000
	s_mov_b64 s[44:45], 0x2000
	s_mov_b64 s[46:47], 0x600
	s_mov_b64 s[48:49], 0x188000
	s_mov_b64 s[56:57], 0x20000
	v_writelane_b32 v255, s79, 28
	s_waitcnt lgkmcnt(0)
	s_barrier
	v_readlane_b32 s16, v253, 4
	v_readlane_b32 s17, v253, 5
	s_branch .LBB0_183

;     __host__ __device__ bool next(int i, Unit& u) const {
;         const long L = (long)i * G + c; if (L >= nwg) return false;
;         int wgid = (int)L; { const int q = nwg / NXCD, r = nwg % NXCD, xcd = wgid % NXCD, off = wgid / NXCD; wgid = (xcd < r ? xcd * (q + 1) : r * (q + 1) + (xcd - r) * q) + off; }
;         const int nig = WGM * nN, gid = wgid / nig, fm = gid * WGM, gsz = (nM - fm) < WGM ? (nM - fm) : WGM;
;         u.pm = fm + ((wgid % nig) % gsz); u.pn = (wgid % nig) / gsz; return true;
;     }
.LBB0_249:
	s_add_i32 s37, s37, 1
	s_mul_i32 s0, s37, s91
	s_mul_hi_u32 s1, s37, s90
	s_add_i32 s1, s1, s0
	s_mul_i32 s0, s37, s90
	s_add_u32 s16, s0, s52
	s_addc_u32 s17, s1, s53
	v_mov_b64_e32 v[0:1], 0xc00
	v_cmp_lt_i64_e64 s[0:1], s[16:17], v[0:1]
	v_mov_b64_e32 v[0:1], 0xbff
	v_cmp_gt_i64_e32 vcc, s[16:17], v[0:1]
	s_cbranch_vccnz .LBB0_251
	s_ashr_i32 s12, s16, 31
	s_lshr_b32 s12, s12, 29
	s_add_i32 s12, s16, s12
	s_ashr_i32 s13, s12, 3
	s_and_b32 s12, s12, -8
	s_sub_i32 s12, s16, s12
	s_cmp_lt_i32 s12, 0
	s_movk_i32 s14, 0x181
	s_cselect_b32 s14, s14, 0x180
	s_mul_i32 s12, s12, s14
	s_add_i32 s12, s12, s13
	s_mul_hi_i32 s13, s12, 0x55555556
	s_lshr_b32 s14, s13, 31
	s_ashr_i32 s13, s13, 6
	s_add_i32 s13, s13, s14
	s_lshl_b32 s14, s13, 2
	s_sub_i32 s15, 64, s14
	s_min_i32 s15, s15, 4
	s_abs_i32 s16, s15
	v_cvt_f32_u32_e32 v0, s16
	s_sub_i32 s18, 0, s16
	s_mulk_i32 s13, 0xc0
	s_sub_i32 s13, s12, s13
	v_rcp_iflag_f32_e32 v0, v0
	s_abs_i32 s12, s13
	s_xor_b32 s17, s13, s15
	s_ashr_i32 s17, s17, 31
	v_mul_f32_e32 v0, 0x4f7ffffe, v0
	v_cvt_u32_f32_e32 v0, v0
	s_nop 0
	v_readfirstlane_b32 s19, v0
	s_mul_i32 s18, s18, s19
	s_mul_hi_u32 s18, s19, s18
	s_add_i32 s19, s19, s18
	s_mul_hi_u32 s18, s12, s19
	s_mul_i32 s19, s18, s16
	s_sub_i32 s12, s12, s19
	s_add_i32 s24, s18, 1
	s_sub_i32 s19, s12, s16
	s_cmp_ge_u32 s12, s16
	s_cselect_b32 s18, s24, s18
	s_cselect_b32 s12, s19, s12
	s_add_i32 s19, s18, 1
	s_cmp_ge_u32 s12, s16
	s_cselect_b32 s12, s19, s18
	s_xor_b32 s12, s12, s17
	s_sub_i32 s12, s12, s17
	s_mul_i32 s15, s12, s15
	s_sub_i32 s13, s13, s15
	s_add_i32 s14, s14, s13

; #define LAS __attribute__((address_space(3)))
; __device__ __forceinline__ f32x4 mfma16(bf16x8 a, bf16x8 b, f32x4 c) { return __builtin_amdgcn_mfma_f32_16x16x32_bf16(a, b, c, 0, 0, 0); }
; template <int RT, class Epi>
; __device__ __forceinline__ void skinny_gemm(const bf16* A, size_t lda, const bf16* Bt, int K, int N, const Epi& epi, int wg, int wg_first, int wg_count, int tid, LAS unsigned char* lds) {
;     const int lane = tid & 63, w = tid >> 6, c = lane & 15, g = lane >> 4;
;     constexpr int NRG = 8 / RT;
;     const int nunit = (N / 32) * NRG, ksteps = K / 256;
;     int me = wg - wg_first; if (me < 0 || me >= wg_count) return;
;     for (int s = me; s < nunit; s += wg_count) {
;         const int n0 = 32 * (s / NRG), r0 = (s % NRG) * (16 * RT);
;         f32x4 acc[RT][2];
; #pragma unroll
;         for (int rt = 0; rt < RT; ++rt) { acc[rt][0] = (f32x4){0.f, 0.f, 0.f, 0.f}; acc[rt][1] = (f32x4){0.f, 0.f, 0.f, 0.f}; }
;         const bf16* ap = A + (size_t)(r0 + c) * lda + (size_t)w * (K / 8) + 8 * g;
;         const bf16* bp = Bt + (size_t)(n0 + c) * K + (size_t)w * (K / 8) + 8 * g;
; #pragma unroll 4
;         for (int ks = 0; ks < ksteps; ++ks) {
;             bf16x8 af[RT], bfr[2];
; #pragma unroll
;             for (int rt = 0; rt < RT; ++rt) af[rt] = *(const bf16x8*)(ap + (size_t)(16 * rt) * lda + 32 * ks);
;             bfr[0] = *(const bf16x8*)(bp + 32 * ks); bfr[1] = *(const bf16x8*)(bp + (size_t)16 * K + 32 * ks);
; #pragma unroll
;             for (int rt = 0; rt < RT; ++rt) { acc[rt][0] = mfma16(af[rt], bfr[0], acc[rt][0]); acc[rt][1] = mfma16(af[rt], bfr[1], acc[rt][1]); }
;         }
.LBB0_259:
	s_cmpk_lt_u32 s52, 0x80
	s_cbranch_scc0 .Ldt_skip
	v_mbcnt_lo_u32_b32 v0, -1, 0
	v_mbcnt_hi_u32_b32 v0, -1, v0
	v_readlane_b32 s0, v254, 0
	v_and_b32_e32 v149, 15, v0
	v_lshlrev_b32_e32 v10, 11, v149
	v_or_b32_e32 v1, s0, v0
	v_ashrrev_i32_e32 v2, 6, v1
	v_ashrrev_i32_e32 v3, 31, v2
	v_bfe_u32 v12, v0, 4, 2
	v_lshl_add_u64 v[4:5], s[2:3], 0, v[10:11]
	v_lshlrev_b64 v[6:7], 8, v[2:3]
	v_lshl_add_u64 v[4:5], v[4:5], 0, v[6:7]
	v_lshlrev_b32_e32 v10, 4, v12
	v_lshl_add_u64 v[4:5], v[4:5], 0, v[10:11]
	s_lshl_b32 s0, s52, 18
	s_sub_u32 s0, s0, 0x2000000
	s_subb_u32 s1, 0, 0
	v_lshl_add_u64 v[4:5], v[4:5], 0, s[0:1]
	s_mov_b64 s[0:1], 0x17500000
	v_lshl_add_u64 v[8:9], v[4:5], 0, s[0:1]
	s_mov_b64 s[0:1], 0x17508000
	v_lshl_add_u64 v[90:91], v[4:5], 0, s[0:1]
	s_mov_b64 s[0:1], 0x17510000
	v_lshl_add_u64 v[92:93], v[4:5], 0, s[0:1]
	s_mov_b64 s[0:1], 0x17518000
	v_lshl_add_u64 v[94:95], v[4:5], 0, s[0:1]
	s_mov_b64 s[0:1], 0x17520000
	v_lshl_add_u64 v[96:97], v[4:5], 0, s[0:1]
	s_mov_b64 s[0:1], 0x17528000
	v_lshl_add_u64 v[98:99], v[4:5], 0, s[0:1]
	s_mov_b64 s[0:1], 0x17530000
	v_lshl_add_u64 v[100:101], v[4:5], 0, s[0:1]
	s_mov_b64 s[0:1], 0x17538000
	v_lshl_add_u64 v[102:103], v[4:5], 0, s[0:1]
	s_mov_b64 s[0:1], 0x17508040
	v_lshl_add_u64 v[104:105], v[4:5], 0, s[0:1]
	s_mov_b64 s[0:1], 0x17510040
	v_lshl_add_u64 v[106:107], v[4:5], 0, s[0:1]
	s_mov_b64 s[0:1], 0x17518040
	v_lshl_add_u64 v[108:109], v[4:5], 0, s[0:1]
	s_mov_b64 s[0:1], 0x17520040
	v_lshl_add_u64 v[110:111], v[4:5], 0, s[0:1]
	s_mov_b64 s[0:1], 0x17528040
	v_lshl_add_u64 v[112:113], v[4:5], 0, s[0:1]
	s_mov_b64 s[0:1], 0x17530040
	v_lshl_add_u64 v[114:115], v[4:5], 0, s[0:1]
	s_mov_b64 s[0:1], 0x17538040
	v_lshl_add_u64 v[116:117], v[4:5], 0, s[0:1]
	s_mov_b64 s[0:1], 0x17508080
	v_lshl_add_u64 v[118:119], v[4:5], 0, s[0:1]
	s_mov_b64 s[0:1], 0x17510080
	v_lshl_add_u64 v[120:121], v[4:5], 0, s[0:1]
	s_mov_b64 s[0:1], 0x17518080
	v_lshl_add_u64 v[122:123], v[4:5], 0, s[0:1]
	s_mov_b64 s[0:1], 0x17520080
	v_lshl_add_u64 v[124:125], v[4:5], 0, s[0:1]
	s_mov_b64 s[0:1], 0x17528080
	v_lshl_add_u64 v[126:127], v[4:5], 0, s[0:1]
	s_mov_b64 s[0:1], 0x17530080
	v_lshl_add_u64 v[128:129], v[4:5], 0, s[0:1]
	s_mov_b64 s[0:1], 0x17538080
	v_lshl_add_u64 v[130:131], v[4:5], 0, s[0:1]
	s_mov_b64 s[0:1], 0x175080c0
	v_lshl_add_u64 v[132:133], v[4:5], 0, s[0:1]
	s_mov_b64 s[0:1], 0x175100c0
	v_lshl_add_u64 v[134:135], v[4:5], 0, s[0:1]
	s_mov_b64 s[0:1], 0x175180c0
	v_lshl_add_u64 v[6:7], s[4:5], 0, v[6:7]
	v_lshlrev_b32_e32 v0, 3, v0
	v_lshl_add_u64 v[136:137], v[4:5], 0, s[0:1]
	s_mov_b64 s[0:1], 0x175200c0
	v_lshl_add_u64 v[88:89], v[6:7], 0, v[10:11]
	v_ashrrev_i32_e32 v6, 2, v1
	v_and_b32_e32 v156, 24, v0
	v_lshl_add_u64 v[138:139], v[4:5], 0, s[0:1]
	s_mov_b64 s[0:1], 0x175280c0
	v_lshlrev_b32_e32 v0, 7, v6
	v_lshlrev_b32_e32 v1, 2, v156
	v_lshl_add_u64 v[140:141], v[4:5], 0, s[0:1]
	s_mov_b64 s[0:1], 0x175300c0
	v_add3_u32 v157, 0, v0, v1
	v_lshl_add_u64 v[142:143], v[4:5], 0, s[0:1]
	s_mov_b64 s[0:1], 0x175380c0
	v_mov_b64_e32 v[0:1], s[2:3]
	v_lshl_add_u64 v[144:145], v[4:5], 0, s[0:1]
	v_mad_i64_i32 v[0:1], s[0:1], v6, s77, v[0:1]
	v_lshl_add_u32 v13, v149, 2, 0
	v_lshlrev_b32_e32 v2, 14, v2
	v_lshlrev_b32_e32 v3, 9, v12
	s_mov_b64 s[0:1], 0x2fe00000
	v_add3_u32 v158, v13, v2, v3
	v_add_u32_e32 v159, 0x10000, v157
	v_add_u32_e32 v160, 0x10010, v157
	v_add_u32_e32 v161, 0x14000, v157
	v_add_u32_e32 v162, 0x14010, v157
	v_add_u32_e32 v163, 0x18000, v157
	v_add_u32_e32 v164, 0x18010, v157
	v_add_u32_e32 v165, 0x1c000, v157
	v_add_u32_e32 v166, 0x1c010, v157
	v_lshl_add_u64 v[146:147], v[0:1], 0, s[0:1]
	s_mul_i32 s0, s52, 0x310000
	s_sub_u32 s0, s0, 0x18800000
	s_subb_u32 s1, 0, 0
	v_lshl_add_u64 v[146:147], v[146:147], 0, s[0:1]
	s_movk_i32 s0, 0x3000
	s_nop 0
	s_nop 0
	s_nop 0
	v_add_u32_e32 v10, s0, v149
	global_load_dwordx4 v[0:3], v[8:9], off
	global_load_dwordx4 v[4:7], v[90:91], off
	v_lshlrev_b64 v[12:13], 11, v[10:11]
	global_load_dwordx4 v[16:19], v[92:93], off
	global_load_dwordx4 v[20:23], v[94:95], off
	global_load_dwordx4 v[24:27], v[96:97], off
	global_load_dwordx4 v[28:31], v[98:99], off
	global_load_dwordx4 v[58:61], v[100:101], off
	global_load_dwordx4 v[66:69], v[102:103], off
	v_lshl_add_u64 v[32:33], v[88:89], 0, v[12:13]
	v_add_co_u32_e32 v56, vcc, 0x8000, v32
	global_load_dwordx4 v[12:15], v[32:33], off
	s_nop 0
	v_addc_co_u32_e32 v57, vcc, 0, v33, vcc
	global_load_dwordx4 v[78:81], v[56:57], off
	global_load_dwordx4 v[82:85], v[104:105], off
	global_load_dwordx4 v[168:171], v[106:107], off
	global_load_dwordx4 v[172:175], v[108:109], off
	global_load_dwordx4 v[188:191], v[110:111], off
	global_load_dwordx4 v[192:195], v[112:113], off
	global_load_dwordx4 v[196:199], v[114:115], off
	global_load_dwordx4 v[200:203], v[116:117], off
	global_load_dwordx4 v[208:211], v[130:131], off
	v_add_u32_e32 v150, 0x3800, v158
	s_nop 0
	v_add_u32_e32 v10, s0, v156
	s_nop 0
	s_nop 0
	s_waitcnt vmcnt(0) lgkmcnt(0)
	v_mfma_f32_16x16x32_bf16 v[34:37], v[0:3], v[12:15], 0
	global_load_dwordx4 v[212:215], v[56:57], off offset:128
	v_mfma_f32_16x16x32_bf16 v[38:41], v[4:7], v[12:15], 0
	v_mfma_f32_16x16x32_bf16 v[42:45], v[16:19], v[12:15], 0
	v_mfma_f32_16x16x32_bf16 v[46:49], v[20:23], v[12:15], 0
	v_mfma_f32_16x16x32_bf16 v[50:53], v[24:27], v[12:15], 0
	v_mfma_f32_16x16x32_bf16 v[62:65], v[28:31], v[12:15], 0
	v_mfma_f32_16x16x32_bf16 v[70:73], v[58:61], v[12:15], 0
	v_mfma_f32_16x16x32_bf16 v[74:77], v[66:69], v[12:15], 0
	v_mfma_f32_16x16x32_bf16 v[12:15], v[16:19], v[78:81], 0
	v_mfma_f32_16x16x32_bf16 v[16:19], v[20:23], v[78:81], 0
	v_mfma_f32_16x16x32_bf16 v[20:23], v[24:27], v[78:81], 0
	v_mfma_f32_16x16x32_bf16 v[24:27], v[28:31], v[78:81], 0
	v_mfma_f32_16x16x32_bf16 v[28:31], v[58:61], v[78:81], 0
	global_load_dwordx4 v[58:61], v[8:9], off offset:64
	v_mfma_f32_16x16x32_bf16 v[0:3], v[0:3], v[78:81], 0
	v_mfma_f32_16x16x32_bf16 v[4:7], v[4:7], v[78:81], 0
	v_mfma_f32_16x16x32_bf16 v[66:69], v[66:69], v[78:81], 0
	global_load_dwordx4 v[78:81], v[32:33], off offset:64
	s_waitcnt vmcnt(0) lgkmcnt(0)
; #define LAS __attribute__((address_space(3)))
; __device__ __forceinline__ f32x4 mfma16(bf16x8 a, bf16x8 b, f32x4 c) { return __builtin_amdgcn_mfma_f32_16x16x32_bf16(a, b, c, 0, 0, 0); }
; __device__ __forceinline__ void sync_threads() { __syncthreads(); }
; template <int RT, class Epi>
; __device__ __forceinline__ void skinny_gemm(const bf16* A, size_t lda, const bf16* Bt, int K, int N, const Epi& epi, int wg, int wg_first, int wg_count, int tid, LAS unsigned char* lds) {
;     ...
; #pragma unroll 4
;         for (int ks = 0; ks < ksteps; ++ks) {
;             bf16x8 af[RT], bfr[2];
; #pragma unroll
;             for (int rt = 0; rt < RT; ++rt) af[rt] = *(const bf16x8*)(ap + (size_t)(16 * rt) * lda + 32 * ks);
;             bfr[0] = *(const bf16x8*)(bp + 32 * ks); bfr[1] = *(const bf16x8*)(bp + (size_t)16 * K + 32 * ks);
; #pragma unroll
;             for (int rt = 0; rt < RT; ++rt) { acc[rt][0] = mfma16(af[rt], bfr[0], acc[rt][0]); acc[rt][1] = mfma16(af[rt], bfr[1], acc[rt][1]); }
;         }
;         LAS float* part = (LAS float*)(lds + w * SK_PART);
; #pragma unroll
;         for (int rt = 0; rt < RT; ++rt)
; #pragma unroll
;             for (int nt = 0; nt < 2; ++nt)
; #pragma unroll
;                 for (int r = 0; r < 4; ++r) part[(16 * rt + 4 * g + r) * 32 + 16 * nt + c] = acc[rt][nt][r];
;         sync_threads();
	v_mfma_f32_16x16x32_bf16 v[34:37], v[58:61], v[78:81], v[34:37]
	v_mfma_f32_16x16x32_bf16 v[38:41], v[82:85], v[78:81], v[38:41]
	v_mfma_f32_16x16x32_bf16 v[42:45], v[168:171], v[78:81], v[42:45]
	v_mfma_f32_16x16x32_bf16 v[46:49], v[172:175], v[78:81], v[46:49]
	v_mfma_f32_16x16x32_bf16 v[50:53], v[188:191], v[78:81], v[50:53]
	v_mfma_f32_16x16x32_bf16 v[62:65], v[192:195], v[78:81], v[62:65]
	v_mfma_f32_16x16x32_bf16 v[70:73], v[196:199], v[78:81], v[70:73]
	v_mfma_f32_16x16x32_bf16 v[74:77], v[200:203], v[78:81], v[74:77]
	global_load_dwordx4 v[78:81], v[56:57], off offset:64
	s_waitcnt vmcnt(0) lgkmcnt(0)
	v_mfma_f32_16x16x32_bf16 v[0:3], v[58:61], v[78:81], v[0:3]
	global_load_dwordx4 v[58:61], v[8:9], off offset:128
	v_mfma_f32_16x16x32_bf16 v[4:7], v[82:85], v[78:81], v[4:7]
	v_mfma_f32_16x16x32_bf16 v[12:15], v[168:171], v[78:81], v[12:15]
	global_load_dwordx4 v[168:171], v[120:121], off
	v_mfma_f32_16x16x32_bf16 v[16:19], v[172:175], v[78:81], v[16:19]
	v_mfma_f32_16x16x32_bf16 v[20:23], v[188:191], v[78:81], v[20:23]
	global_load_dwordx4 v[188:191], v[124:125], off
	v_mfma_f32_16x16x32_bf16 v[24:27], v[192:195], v[78:81], v[24:27]
	v_mfma_f32_16x16x32_bf16 v[28:31], v[196:199], v[78:81], v[28:31]
	v_mfma_f32_16x16x32_bf16 v[84:87], v[200:203], v[78:81], v[66:69]
	global_load_dwordx4 v[78:81], v[118:119], off
	global_load_dwordx4 v[200:203], v[128:129], off
	s_nop 0
	global_load_dwordx4 v[66:69], v[32:33], off offset:128
	s_waitcnt vmcnt(0) lgkmcnt(0)
	v_mfma_f32_16x16x32_bf16 v[172:175], v[168:171], v[66:69], v[42:45]
	s_nop 2
	global_load_dwordx4 v[42:45], v[122:123], off
	v_mfma_f32_16x16x32_bf16 v[192:195], v[188:191], v[66:69], v[50:53]
	s_nop 2
	global_load_dwordx4 v[50:53], v[126:127], off
	v_mfma_f32_16x16x32_bf16 v[34:37], v[58:61], v[66:69], v[34:37]
	v_mfma_f32_16x16x32_bf16 v[38:41], v[78:81], v[66:69], v[38:41]
	s_waitcnt vmcnt(0) lgkmcnt(0)
	v_mfma_f32_16x16x32_bf16 v[46:49], v[42:45], v[66:69], v[46:49]
	v_mfma_f32_16x16x32_bf16 v[196:199], v[50:53], v[66:69], v[62:65]
	v_mfma_f32_16x16x32_bf16 v[204:207], v[200:203], v[66:69], v[70:73]
	v_mfma_f32_16x16x32_bf16 v[72:75], v[208:211], v[66:69], v[74:77]
	v_mfma_f32_16x16x32_bf16 v[64:67], v[58:61], v[212:215], v[0:3]
	global_load_dwordx4 v[56:59], v[56:57], off offset:192
	v_mfma_f32_16x16x32_bf16 v[68:71], v[78:81], v[212:215], v[4:7]
	v_mfma_f32_16x16x32_bf16 v[76:79], v[168:171], v[212:215], v[12:15]
	global_load_dwordx4 v[168:171], v[8:9], off offset:192
	v_mfma_f32_16x16x32_bf16 v[60:63], v[188:191], v[212:215], v[20:23]
	global_load_dwordx4 v[188:191], v[132:133], off
	v_mfma_f32_16x16x32_bf16 v[0:3], v[200:203], v[212:215], v[28:31]
	global_load_dwordx4 v[200:203], v[134:135], off
	v_mfma_f32_16x16x32_bf16 v[80:83], v[42:45], v[212:215], v[16:19]
	s_nop 2
	global_load_dwordx4 v[16:19], v[32:33], off offset:192
	v_mfma_f32_16x16x32_bf16 v[4:7], v[208:211], v[212:215], v[84:87]
	global_load_dwordx4 v[208:211], v[138:139], off
	s_waitcnt vmcnt(0) lgkmcnt(0)
	v_mfma_f32_16x16x32_bf16 v[12:15], v[168:171], v[16:19], v[34:37]
	v_mfma_f32_16x16x32_bf16 v[40:43], v[188:191], v[16:19], v[38:41]
	v_mfma_f32_16x16x32_bf16 v[36:39], v[200:203], v[16:19], v[172:175]
	s_nop 2
	global_load_dwordx4 v[172:175], v[136:137], off
	v_mfma_f32_16x16x32_bf16 v[52:55], v[50:53], v[212:215], v[24:27]
	v_mfma_f32_16x16x32_bf16 v[28:31], v[208:211], v[16:19], v[192:195]
	s_nop 2
	global_load_dwordx4 v[192:195], v[140:141], off
	s_waitcnt vmcnt(0) lgkmcnt(0)
	v_mfma_f32_16x16x32_bf16 v[32:35], v[172:175], v[16:19], v[46:49]
	s_nop 2
	global_load_dwordx4 v[48:51], v[142:143], off
	global_load_dwordx4 v[44:47], v[144:145], off
	v_mfma_f32_16x16x32_bf16 v[84:87], v[168:171], v[56:59], v[64:67]
	v_mfma_f32_16x16x32_bf16 v[24:27], v[192:195], v[16:19], v[196:199]
	s_waitcnt vmcnt(0) lgkmcnt(0)
	v_mfma_f32_16x16x32_bf16 v[20:23], v[48:51], v[16:19], v[204:207]
	v_mfma_f32_16x16x32_bf16 v[16:19], v[44:47], v[16:19], v[72:75]
	v_mfma_f32_16x16x32_bf16 v[64:67], v[172:175], v[56:59], v[80:83]
	v_mfma_f32_16x16x32_bf16 v[60:63], v[208:211], v[56:59], v[60:63]
	s_nop 1
	v_add_u32_e32 v80, 0x1800, v158
	v_add_u32_e32 v81, 0x2000, v158
	v_add_u32_e32 v82, 0x2800, v158
	v_mfma_f32_16x16x32_bf16 v[52:55], v[192:195], v[56:59], v[52:55]
	v_add_u32_e32 v83, 0x3000, v158
	v_mfma_f32_16x16x32_bf16 v[0:3], v[48:51], v[56:59], v[0:3]
	v_mfma_f32_16x16x32_bf16 v[4:7], v[44:47], v[56:59], v[4:7]
	v_mfma_f32_16x16x32_bf16 v[72:75], v[188:191], v[56:59], v[68:71]
	v_mfma_f32_16x16x32_bf16 v[68:71], v[200:203], v[56:59], v[76:79]
	s_nop 2
	v_add_u32_e32 v78, 0x800, v158
	v_add_u32_e32 v79, 0x1000, v158
	ds_write2_b32 v158, v12, v84 offset1:16
	ds_write2_b32 v158, v13, v85 offset0:32 offset1:48
	ds_write2_b32 v158, v14, v86 offset0:64 offset1:80
	ds_write2_b32 v158, v15, v87 offset0:96 offset1:112
	ds_write2_b32 v78, v40, v72 offset1:16
	ds_write2_b32 v78, v41, v73 offset0:32 offset1:48
	ds_write2_b32 v78, v42, v74 offset0:64 offset1:80
	ds_write2_b32 v78, v43, v75 offset0:96 offset1:112
	ds_write2_b32 v79, v36, v68 offset1:16
	ds_write2_b32 v79, v37, v69 offset0:32 offset1:48
	ds_write2_b32 v79, v38, v70 offset0:64 offset1:80
	ds_write2_b32 v79, v39, v71 offset0:96 offset1:112
	ds_write2_b32 v80, v32, v64 offset1:16
	ds_write2_b32 v80, v33, v65 offset0:32 offset1:48
	ds_write2_b32 v80, v34, v66 offset0:64 offset1:80
	ds_write2_b32 v80, v35, v67 offset0:96 offset1:112
	ds_write2_b32 v81, v28, v60 offset1:16
	ds_write2_b32 v81, v29, v61 offset0:32 offset1:48
	ds_write2_b32 v81, v30, v62 offset0:64 offset1:80
	ds_write2_b32 v81, v31, v63 offset0:96 offset1:112
	ds_write2_b32 v82, v24, v52 offset1:16
	ds_write2_b32 v82, v25, v53 offset0:32 offset1:48
	ds_write2_b32 v82, v26, v54 offset0:64 offset1:80
	ds_write2_b32 v82, v27, v55 offset0:96 offset1:112
	ds_write2_b32 v83, v20, v0 offset1:16
	ds_write2_b32 v83, v21, v1 offset0:32 offset1:48
	ds_write2_b32 v83, v22, v2 offset0:64 offset1:80
	ds_write2_b32 v83, v23, v3 offset0:96 offset1:112
	ds_write2_b32 v150, v16, v4 offset1:16
	ds_write2_b32 v150, v17, v5 offset0:32 offset1:48
	ds_write2_b32 v150, v18, v6 offset0:64 offset1:80
	ds_write2_b32 v150, v19, v7 offset0:96 offset1:112
	s_waitcnt lgkmcnt(0)
	s_barrier
; #define LAS __attribute__((address_space(3)))
; __device__ __forceinline__ void sync_threads() { __syncthreads(); }
; template <int RT, class Epi>
; __device__ __forceinline__ void skinny_gemm(const bf16* A, size_t lda, const bf16* Bt, int K, int N, const Epi& epi, int wg, int wg_first, int wg_count, int tid, LAS unsigned char* lds) {
;     ...
;         sync_threads();
;         if (RT == 8 || tid < 64 * RT) {
;             const int row = tid >> 2, c8 = (tid & 3) * 8;
;             f32x4 v0 = (f32x4){0.f, 0.f, 0.f, 0.f}, v1 = (f32x4){0.f, 0.f, 0.f, 0.f};
; #pragma unroll
;             for (int ww = 0; ww < 8; ++ww) { const LAS float* pp = (const LAS float*)(lds + ww * SK_PART) + row * 32 + c8; v0 = v0 + *(const LAS f32x4*)pp; v1 = v1 + *(const LAS f32x4*)(pp + 4); }
;             epi(r0 + row, n0 + c8, v0, v1);
;         }
;         sync_threads();
;     }
; }
	ds_read_b128 v[0:3], v157
	ds_read_b128 v[4:7], v157 offset:16
	ds_read_b128 v[12:15], v157 offset:16384
	ds_read_b128 v[16:19], v157 offset:16400
	ds_read_b128 v[20:23], v157 offset:32768
	ds_read_b128 v[24:27], v157 offset:32784
	ds_read_b128 v[28:31], v157 offset:49152
	ds_read_b128 v[32:35], v157 offset:49168
	ds_read_b128 v[36:39], v159
	ds_read_b128 v[40:43], v160
	ds_read_b128 v[44:47], v161
	ds_read_b128 v[48:51], v162
	ds_read_b128 v[52:55], v163
	ds_read_b128 v[56:59], v164
	ds_read_b128 v[60:63], v165
	ds_read_b128 v[64:67], v166
	s_waitcnt lgkmcnt(14)
	v_pk_add_f32 v[2:3], v[2:3], 0 op_sel_hi:[1,0]
	v_pk_add_f32 v[0:1], v[0:1], 0 op_sel_hi:[1,0]
	v_pk_add_f32 v[6:7], v[6:7], 0 op_sel_hi:[1,0]
	v_pk_add_f32 v[4:5], v[4:5], 0 op_sel_hi:[1,0]
	s_waitcnt lgkmcnt(13)
	v_pk_add_f32 v[2:3], v[2:3], v[14:15]
	v_pk_add_f32 v[0:1], v[0:1], v[12:13]
	s_waitcnt lgkmcnt(12)
	v_pk_add_f32 v[6:7], v[6:7], v[18:19]
	v_pk_add_f32 v[4:5], v[4:5], v[16:17]
	s_waitcnt lgkmcnt(11)
	v_pk_add_f32 v[2:3], v[2:3], v[22:23]
	v_pk_add_f32 v[0:1], v[0:1], v[20:21]
	s_waitcnt lgkmcnt(10)
	v_pk_add_f32 v[6:7], v[6:7], v[26:27]
	v_pk_add_f32 v[4:5], v[4:5], v[24:25]
	s_waitcnt lgkmcnt(9)
	v_pk_add_f32 v[2:3], v[2:3], v[30:31]
	v_pk_add_f32 v[0:1], v[0:1], v[28:29]
	s_waitcnt lgkmcnt(8)
	v_pk_add_f32 v[6:7], v[6:7], v[34:35]
	v_pk_add_f32 v[4:5], v[4:5], v[32:33]
	s_waitcnt lgkmcnt(7)
	v_pk_add_f32 v[2:3], v[2:3], v[38:39]
	v_pk_add_f32 v[0:1], v[0:1], v[36:37]
	s_waitcnt lgkmcnt(6)
	v_pk_add_f32 v[6:7], v[6:7], v[42:43]
	v_pk_add_f32 v[4:5], v[4:5], v[40:41]
	s_waitcnt lgkmcnt(5)
	v_pk_add_f32 v[2:3], v[2:3], v[46:47]
	v_pk_add_f32 v[0:1], v[0:1], v[44:45]
	s_waitcnt lgkmcnt(4)
	v_pk_add_f32 v[6:7], v[6:7], v[50:51]
	v_pk_add_f32 v[4:5], v[4:5], v[48:49]
	s_waitcnt lgkmcnt(3)
	v_pk_add_f32 v[2:3], v[2:3], v[54:55]
	v_pk_add_f32 v[0:1], v[0:1], v[52:53]
	v_lshl_add_u64 v[76:77], v[10:11], 1, v[146:147]
	s_waitcnt lgkmcnt(2)
	v_pk_add_f32 v[6:7], v[6:7], v[58:59]
	v_pk_add_f32 v[4:5], v[4:5], v[56:57]
	s_waitcnt lgkmcnt(1)
	v_pk_add_f32 v[2:3], v[2:3], v[62:63]
	v_pk_add_f32 v[0:1], v[0:1], v[60:61]
	s_waitcnt lgkmcnt(0)
	v_pk_add_f32 v[6:7], v[6:7], v[66:67]
	v_pk_add_f32 v[4:5], v[4:5], v[64:65]
	v_cvt_pk_bf16_f32 v0, v0, v1
	v_cvt_pk_bf16_f32 v1, v2, v3
	v_cvt_pk_bf16_f32 v3, v6, v7
	s_nop 0
	v_cvt_pk_bf16_f32 v2, v4, v5
	global_store_dwordx4 v[76:77], v[0:3], off
	s_waitcnt lgkmcnt(0)
	s_barrier
